# all 128 forget-gate log sites simplified (previous: 112)
# speedup vs baseline: 1.0080x; 1.0024x over previous
; __device__ __forceinline__ float silu_f(float x) { return x * __builtin_amdgcn_rcpf(1.f + __expf(-x)); }
; __device__ __forceinline__ v4u pack8(const float (&y)[8]) { return (v4u){pk2(y[0], y[1]), pk2(y[2], y[3]), pk2(y[4], y[5]), pk2(y[6], y[7])}; }
;     __device__ __forceinline__ void operator()(const f32x4 (&acc)[2][2][4][2], const pg8::Unit& u, int wr, int wc, int fr, int fq) const {
;     ...
;                         const int row = lrow0 + ai * 128 + m * 16; const size_t off = (size_t)row * 1024 + c;
;                         const f32x4 v0 = acc[ai][bj][m][0] * rs[ai][m], v1 = acc[ai][bj][m][1] * rs[ai][m];
;                         const float v[8] = {v0[0], v0[1], v0[2], v0[3], v1[0], v1[1], v1[2], v1[3]};
;                         float y[8];
;                         if (region == 0) {
; #pragma unroll
;                             for (int j = 0; j < 8; ++j) y[j] = silu_f(v[j]);
;                             *(v4u*)(o0 + off) = pack8(y);
;                         } else if (region == 1) {
;                             float lf[8];
; #pragma unroll
;                             for (int j = 0; j < 8; ++j) {
;                                 const float om = 1.f - lb[j];
;                                 const float fc = fminf(fmaxf(v[j], -80.f), 80.f);
;                                 const float e = __expf(-fc), sg = __builtin_amdgcn_rcpf(1.f + e);
;                                 y[j] = om * e * sg;
;                                 lf[j] = __logf(fmaxf(lb[j] + om * sg, 1e-30f));
;                             }
;                             *(v4u*)(o1 + off) = pack8(y);
;                             *(f32x4*)(of + off) = (f32x4){lf[0], lf[1], lf[2], lf[3]}; *(f32x4*)(of + off + 4) = (f32x4){lf[4], lf[5], lf[6], lf[7]};
.LBB0_995:
	s_nop 1
	v_fmamk_f32 v74, v199, 0x3a800000, v139
	s_mov_b64 s[0:1], 0x2c000
	s_nop 0
	v_rsq_f32_e32 v76, v74
	v_lshlrev_b64 v[74:75], 10, v[178:179]
	v_lshl_add_u64 v[74:75], v[74:75], 0, s[0:1]
	v_or_b32_e32 v78, v74, v198
	s_nop 0
	v_mov_b32_e32 v79, v75
	v_pk_mul_f32 v[80:81], v[72:73], v[76:77] op_sel_hi:[1,0]
	v_pk_mul_f32 v[86:87], v[70:71], v[76:77] op_sel_hi:[1,0]
	v_pk_mul_f32 v[70:71], v[68:69], v[76:77] op_sel_hi:[1,0]
	v_pk_mul_f32 v[72:73], v[66:67], v[76:77] op_sel_hi:[1,0]
	s_and_b64 vcc, exec, s[44:45]
	s_mov_b64 s[0:1], -1
	s_cbranch_vccnz .LBB0_1004
	s_and_b64 vcc, exec, s[42:43]
	s_cbranch_vccnz .LBB0_998
	v_max_f32_e32 v66, v86, v86
	s_mov_b32 s39, 0xc2a00000
	v_med3_f32 v66, v66, s39, v195
	v_mul_f32_e32 v66, 0xbfb8aa3b, v66
	v_exp_f32_e32 v66, v66
	v_pk_add_f32 v[94:95], v[176:177], 1.0 op_sel_hi:[1,0] neg_lo:[1,0] neg_hi:[1,0]
	s_mov_b32 s13, 0x3f317217
	s_mov_b32 s15, 0x7f800000
	v_add_f32_e32 v67, 1.0, v66
	v_rcp_f32_e32 v68, v67
	v_max_f32_e32 v67, v87, v87
	v_med3_f32 v67, v67, s39, v195
	v_mul_f32_e32 v67, 0xbfb8aa3b, v67
	v_exp_f32_e32 v67, v67
	v_fmac_f32_e32 v176, v68, v94
	v_pk_add_f32 v[102:103], v[174:175], 1.0 op_sel_hi:[1,0] neg_lo:[1,0] neg_hi:[1,0]
	v_pk_add_f32 v[104:105], v[172:173], 1.0 op_sel_hi:[1,0] neg_lo:[1,0] neg_hi:[1,0]
	v_add_f32_e32 v69, 1.0, v67
	v_rcp_f32_e32 v69, v69
	v_pk_mul_f32 v[66:67], v[66:67], v[94:95]
	v_pk_add_f32 v[112:113], v[170:171], 1.0 op_sel_hi:[1,0] neg_lo:[1,0] neg_hi:[1,0]
	v_pk_mul_f32 v[88:89], v[68:69], v[66:67]
	v_max_f32_e32 v66, 0xda24260, v176
	v_fmac_f32_e32 v177, v69, v95
	s_nop 0
	v_log_f32_e32 v66, v66
	s_nop 0
	v_mul_f32_e32 v67, 0x3f317217, v66
	v_fma_f32 v67, v66, s13, -v67
	v_fmac_f32_e32 v67, 0x3377d1cf, v66
	v_fmac_f32_e32 v67, 0x3f317217, v66
	s_nop 1
	v_mov_b32_e32 v66, v67
	v_max_f32_e32 v67, 0xda24260, v177
	s_nop 1
	v_log_f32_e32 v67, v67
	s_nop 0
	v_mul_f32_e32 v68, 0x3f317217, v67
	v_fma_f32 v68, v67, s13, -v68
	v_fmac_f32_e32 v68, 0x3377d1cf, v67
	v_fmac_f32_e32 v68, 0x3f317217, v67
	s_nop 1
	v_mov_b32_e32 v67, v68
	v_max_f32_e32 v68, v80, v80
	v_med3_f32 v68, v68, s39, v195
	v_mul_f32_e32 v68, 0xbfb8aa3b, v68
	v_exp_f32_e32 v68, v68
	s_nop 0
	v_add_f32_e32 v69, 1.0, v68
	v_rcp_f32_e32 v96, v69
	v_max_f32_e32 v69, v81, v81
	v_med3_f32 v69, v69, s39, v195
	v_mul_f32_e32 v69, 0xbfb8aa3b, v69
	v_exp_f32_e32 v69, v69
	v_fmac_f32_e32 v174, v96, v102
	v_add_f32_e32 v77, 1.0, v69
	v_rcp_f32_e32 v97, v77
	v_pk_mul_f32 v[68:69], v[68:69], v[102:103]
	v_fmac_f32_e32 v175, v97, v103
	v_pk_mul_f32 v[94:95], v[96:97], v[68:69]
	v_max_f32_e32 v68, 0xda24260, v174
	s_nop 1
	v_log_f32_e32 v68, v68
	s_nop 0
	v_mul_f32_e32 v69, 0x3f317217, v68
	v_fma_f32 v69, v68, s13, -v69
	v_fmac_f32_e32 v69, 0x3377d1cf, v68
	v_fmac_f32_e32 v69, 0x3f317217, v68
	s_nop 1
	v_mov_b32_e32 v68, v69
	v_max_f32_e32 v69, 0xda24260, v175
	s_nop 1
	v_log_f32_e32 v69, v69
	s_nop 0
	v_mul_f32_e32 v77, 0x3f317217, v69
	v_fma_f32 v77, v69, s13, -v77
	v_fmac_f32_e32 v77, 0x3377d1cf, v69
	v_fmac_f32_e32 v77, 0x3f317217, v69
	s_nop 1
	v_mov_b32_e32 v69, v77
	v_max_f32_e32 v77, v72, v72
	v_med3_f32 v77, v77, s39, v195
	v_mul_f32_e32 v77, 0xbfb8aa3b, v77
	v_exp_f32_e32 v96, v77
	s_nop 0
	v_add_f32_e32 v77, 1.0, v96
	v_rcp_f32_e32 v102, v77
	v_max_f32_e32 v77, v73, v73
	v_med3_f32 v77, v77, s39, v195
	v_mul_f32_e32 v77, 0xbfb8aa3b, v77
	v_exp_f32_e32 v97, v77
	v_fmac_f32_e32 v172, v102, v104
	v_add_f32_e32 v77, 1.0, v97
	v_rcp_f32_e32 v103, v77
	v_max_f32_e32 v77, 0xda24260, v172
	v_pk_mul_f32 v[96:97], v[96:97], v[104:105]
	v_fmac_f32_e32 v173, v103, v105
	v_log_f32_e32 v77, v77
	v_pk_mul_f32 v[96:97], v[102:103], v[96:97]
	v_mul_f32_e32 v85, 0x3f317217, v77
	v_fma_f32 v85, v77, s13, -v85
	v_fmac_f32_e32 v85, 0x3377d1cf, v77
	v_fmac_f32_e32 v85, 0x3f317217, v77
	s_nop 1
	v_mov_b32_e32 v77, v85
	v_mov_b32_e32 v102, v77
	v_max_f32_e32 v77, 0xda24260, v173
	s_nop 1
	v_log_f32_e32 v77, v77
	s_nop 0
	v_mul_f32_e32 v85, 0x3f317217, v77
	v_fma_f32 v85, v77, s13, -v85
	v_fmac_f32_e32 v85, 0x3377d1cf, v77
	v_fmac_f32_e32 v85, 0x3f317217, v77
	s_nop 1
	v_mov_b32_e32 v77, v85
	v_mov_b32_e32 v103, v77
	v_max_f32_e32 v77, v70, v70
	v_med3_f32 v77, v77, s39, v195
	v_mul_f32_e32 v77, 0xbfb8aa3b, v77
	v_exp_f32_e32 v104, v77
	s_nop 0
	v_add_f32_e32 v77, 1.0, v104
	v_rcp_f32_e32 v110, v77
	v_max_f32_e32 v77, v71, v71
	v_med3_f32 v77, v77, s39, v195
	v_mul_f32_e32 v77, 0xbfb8aa3b, v77
	v_exp_f32_e32 v105, v77
	v_fmac_f32_e32 v170, v110, v112
	v_add_f32_e32 v77, 1.0, v105
	v_rcp_f32_e32 v111, v77
	v_max_f32_e32 v77, 0xda24260, v170
	v_pk_mul_f32 v[104:105], v[104:105], v[112:113]
	v_fmac_f32_e32 v171, v111, v113
	v_log_f32_e32 v77, v77
	v_pk_mul_f32 v[118:119], v[110:111], v[104:105]
	v_cvt_pk_bf16_f32 v110, v88, v89
	v_cvt_pk_bf16_f32 v111, v94, v95
	v_mul_f32_e32 v85, 0x3f317217, v77
	v_fma_f32 v85, v77, s13, -v85
	v_fmac_f32_e32 v85, 0x3377d1cf, v77
	v_fmac_f32_e32 v85, 0x3f317217, v77
	v_cvt_pk_bf16_f32 v112, v96, v97
	v_cvt_pk_bf16_f32 v113, v118, v119
	v_mov_b32_e32 v77, v85
	v_mov_b32_e32 v104, v77
	v_max_f32_e32 v77, 0xda24260, v171
	s_nop 1
	v_log_f32_e32 v77, v77
	s_nop 0
	v_mul_f32_e32 v85, 0x3f317217, v77
	v_fma_f32 v85, v77, s13, -v85
	v_fmac_f32_e32 v85, 0x3377d1cf, v77
	v_fmac_f32_e32 v85, 0x3f317217, v77
	s_nop 1
	v_mov_b32_e32 v77, v85
	v_readlane_b32 s0, v253, 0
	v_readlane_b32 s1, v253, 1
	v_mov_b32_e32 v105, v77
	v_lshl_add_u64 v[88:89], v[78:79], 1, s[0:1]
	global_store_dwordx4 v[88:89], v[110:113], off
	v_lshl_add_u64 v[88:89], v[78:79], 2, s[2:3]
	s_mov_b64 s[0:1], 0
	global_store_dwordx4 v[88:89], v[66:69], off
	global_store_dwordx4 v[88:89], v[102:105], off offset:16

; __device__ __forceinline__ v4u pack8(const float (&y)[8]) { return (v4u){pk2(y[0], y[1]), pk2(y[2], y[3]), pk2(y[4], y[5]), pk2(y[6], y[7])}; }
;     __device__ __forceinline__ void operator()(const f32x4 (&acc)[2][2][4][2], const pg8::Unit& u, int wr, int wc, int fr, int fq) const {
;     ...
;                         } else if (region == 1) {
;                             float lf[8];
; #pragma unroll
;                             for (int j = 0; j < 8; ++j) {
;                                 const float om = 1.f - lb[j];
;                                 const float fc = fminf(fmaxf(v[j], -80.f), 80.f);
;                                 const float e = __expf(-fc), sg = __builtin_amdgcn_rcpf(1.f + e);
;                                 y[j] = om * e * sg;
;                                 lf[j] = __logf(fmaxf(lb[j] + om * sg, 1e-30f));
;                             }
;                             *(v4u*)(o1 + off) = pack8(y);
;                             *(f32x4*)(of + off) = (f32x4){lf[0], lf[1], lf[2], lf[3]}; *(f32x4*)(of + off + 4) = (f32x4){lf[4], lf[5], lf[6], lf[7]};
.LBB0_1088:
	s_and_b64 vcc, exec, s[42:43]
	s_cbranch_vccnz .LBB0_1090
	v_max_f32_e32 v2, v12, v12
	s_mov_b32 s28, 0xc2a00000
	v_med3_f32 v2, v2, s28, v195
	v_mul_f32_e32 v2, 0xbfb8aa3b, v2
	v_exp_f32_e32 v2, v2
	v_pk_add_f32 v[16:17], v[72:73], 1.0 op_sel_hi:[1,0] neg_lo:[1,0] neg_hi:[1,0]
	s_mov_b32 s13, 0x3f317217
	s_mov_b32 s15, 0x7f800000
	v_add_f32_e32 v3, 1.0, v2
	v_rcp_f32_e32 v4, v3
	v_max_f32_e32 v3, v13, v13
	v_med3_f32 v3, v3, s28, v195
	v_mul_f32_e32 v3, 0xbfb8aa3b, v3
	v_exp_f32_e32 v3, v3
	v_fmac_f32_e32 v72, v4, v16
	v_pk_add_f32 v[20:21], v[70:71], 1.0 op_sel_hi:[1,0] neg_lo:[1,0] neg_hi:[1,0]
	v_pk_add_f32 v[22:23], v[68:69], 1.0 op_sel_hi:[1,0] neg_lo:[1,0] neg_hi:[1,0]
	v_add_f32_e32 v5, 1.0, v3
	v_rcp_f32_e32 v5, v5
	v_pk_mul_f32 v[2:3], v[2:3], v[16:17]
	v_pk_add_f32 v[26:27], v[66:67], 1.0 op_sel_hi:[1,0] neg_lo:[1,0] neg_hi:[1,0]
	v_pk_mul_f32 v[14:15], v[4:5], v[2:3]
	v_max_f32_e32 v2, 0xda24260, v72
	v_fmac_f32_e32 v73, v5, v17
	v_cvt_pk_bf16_f32 v14, v14, v15
	v_log_f32_e32 v2, v2
	s_nop 0
	v_mul_f32_e32 v3, 0x3f317217, v2
	v_fma_f32 v3, v2, s13, -v3
	v_fmac_f32_e32 v3, 0x3377d1cf, v2
	v_fmac_f32_e32 v3, 0x3f317217, v2
	s_nop 1
	v_mov_b32_e32 v2, v3
	v_max_f32_e32 v3, 0xda24260, v73
	s_nop 1
	v_log_f32_e32 v3, v3
	s_nop 0
	v_mul_f32_e32 v4, 0x3f317217, v3
	v_fma_f32 v4, v3, s13, -v4
	v_fmac_f32_e32 v4, 0x3377d1cf, v3
	v_fmac_f32_e32 v4, 0x3f317217, v3
	s_nop 1
	v_mov_b32_e32 v3, v4
	v_max_f32_e32 v4, v10, v10
	v_med3_f32 v4, v4, s28, v195
	v_mul_f32_e32 v4, 0xbfb8aa3b, v4
	v_exp_f32_e32 v4, v4
	s_nop 0
	v_add_f32_e32 v5, 1.0, v4
	v_rcp_f32_e32 v18, v5
	v_max_f32_e32 v5, v11, v11
	v_med3_f32 v5, v5, s28, v195
	v_mul_f32_e32 v5, 0xbfb8aa3b, v5
	v_exp_f32_e32 v5, v5
	v_fmac_f32_e32 v70, v18, v20
	v_add_f32_e32 v16, 1.0, v5
	v_rcp_f32_e32 v19, v16
	v_pk_mul_f32 v[4:5], v[4:5], v[20:21]
	v_fmac_f32_e32 v71, v19, v21
	v_pk_mul_f32 v[16:17], v[18:19], v[4:5]
	v_max_f32_e32 v4, 0xda24260, v70
	v_cvt_pk_bf16_f32 v15, v16, v17
	s_nop 0
	v_log_f32_e32 v4, v4
	s_nop 0
	v_mul_f32_e32 v5, 0x3f317217, v4
	v_fma_f32 v5, v4, s13, -v5
	v_fmac_f32_e32 v5, 0x3377d1cf, v4
	v_fmac_f32_e32 v5, 0x3f317217, v4
	s_nop 1
	v_mov_b32_e32 v4, v5
	v_max_f32_e32 v5, 0xda24260, v71
	s_nop 1
	v_log_f32_e32 v5, v5
	s_nop 0
	v_mul_f32_e32 v18, 0x3f317217, v5
	v_fma_f32 v18, v5, s13, -v18
	v_fmac_f32_e32 v18, 0x3377d1cf, v5
	v_fmac_f32_e32 v18, 0x3f317217, v5
	s_nop 1
	v_mov_b32_e32 v5, v18
	v_max_f32_e32 v18, v8, v8
	v_med3_f32 v18, v18, s28, v195
	v_mul_f32_e32 v18, 0xbfb8aa3b, v18
	v_exp_f32_e32 v18, v18
	s_nop 0
	v_add_f32_e32 v19, 1.0, v18
	v_rcp_f32_e32 v20, v19
	v_max_f32_e32 v19, v9, v9
	v_med3_f32 v19, v19, s28, v195
	v_mul_f32_e32 v19, 0xbfb8aa3b, v19
	v_exp_f32_e32 v19, v19
	v_fmac_f32_e32 v68, v20, v22
	v_add_f32_e32 v21, 1.0, v19
	v_rcp_f32_e32 v21, v21
	v_pk_mul_f32 v[18:19], v[18:19], v[22:23]
	v_fmac_f32_e32 v69, v21, v23
	v_pk_mul_f32 v[24:25], v[20:21], v[18:19]
	v_max_f32_e32 v18, 0xda24260, v68
	v_cvt_pk_bf16_f32 v16, v24, v25
	s_nop 0
	v_log_f32_e32 v18, v18
	s_nop 0
	v_mul_f32_e32 v19, 0x3f317217, v18
	v_fma_f32 v19, v18, s13, -v19
	v_fmac_f32_e32 v19, 0x3377d1cf, v18
	v_fmac_f32_e32 v19, 0x3f317217, v18
	s_nop 1
	v_mov_b32_e32 v18, v19
	v_max_f32_e32 v19, 0xda24260, v69
	s_nop 1
	v_log_f32_e32 v19, v19
	s_nop 0
	v_mul_f32_e32 v20, 0x3f317217, v19
	v_fma_f32 v20, v19, s13, -v20
	v_fmac_f32_e32 v20, 0x3377d1cf, v19
	v_fmac_f32_e32 v20, 0x3f317217, v19
	s_nop 1
	v_mov_b32_e32 v19, v20
	v_max_f32_e32 v20, v6, v6
	v_med3_f32 v20, v20, s28, v195
	v_mul_f32_e32 v20, 0xbfb8aa3b, v20
	v_exp_f32_e32 v20, v20
	s_nop 0
	v_add_f32_e32 v21, 1.0, v20
	v_rcp_f32_e32 v22, v21
	v_max_f32_e32 v21, v7, v7
	v_med3_f32 v21, v21, s28, v195
	v_mul_f32_e32 v21, 0xbfb8aa3b, v21
	v_exp_f32_e32 v21, v21
	v_fmac_f32_e32 v66, v22, v26
	v_add_f32_e32 v23, 1.0, v21
	v_rcp_f32_e32 v23, v23
	v_pk_mul_f32 v[20:21], v[20:21], v[26:27]
	v_fmac_f32_e32 v67, v23, v27
	v_pk_mul_f32 v[28:29], v[22:23], v[20:21]
	v_max_f32_e32 v20, 0xda24260, v66
	v_cvt_pk_bf16_f32 v17, v28, v29
	s_nop 0
	v_log_f32_e32 v20, v20
	s_nop 0
	v_mul_f32_e32 v21, 0x3f317217, v20
	v_fma_f32 v21, v20, s13, -v21
	v_fmac_f32_e32 v21, 0x3377d1cf, v20
	v_fmac_f32_e32 v21, 0x3f317217, v20
	s_nop 1
	v_mov_b32_e32 v20, v21
	v_max_f32_e32 v21, 0xda24260, v67
	s_nop 1
	v_log_f32_e32 v21, v21
	s_nop 0
	v_mul_f32_e32 v22, 0x3f317217, v21
	v_fma_f32 v22, v21, s13, -v22
	v_fmac_f32_e32 v22, 0x3377d1cf, v21
	v_fmac_f32_e32 v22, 0x3f317217, v21
	s_nop 1
	v_mov_b32_e32 v21, v22
	v_readlane_b32 s0, v253, 0
	v_readlane_b32 s1, v253, 1
	s_nop 0
	v_lshl_add_u64 v[22:23], v[74:75], 1, s[0:1]
	global_store_dwordx4 v[22:23], v[14:17], off
	s_mov_b64 s[0:1], 0
	s_nop 0
	v_lshl_add_u64 v[14:15], v[74:75], 2, s[2:3]
	global_store_dwordx4 v[14:15], v[2:5], off
	global_store_dwordx4 v[14:15], v[18:21], off offset:16
